# nt hint also on the residual reads of the two FFN down-GEMM epilogues (x / x2 f32, read once); on top of v015
# speedup vs baseline: 1.0063x; 1.0063x over previous
; __host__ __device__ __forceinline__ size_t blk_off(int r, int k, int KT) { return ((size_t)((r >> 8) * KT + (k >> 6)) * 256 + (size_t)(r & 255)) * 64 + (size_t)(k & 63); }
; __device__ __forceinline__ unsigned cvt_pk_bf16(float lo, float hi) { unsigned r; asm volatile("v_cvt_pk_bf16_f32 %0, %1, %2" : "=v"(r) : "v"(lo), "v"(hi)); return r; }
;     __device__ __forceinline__ void operator()(const i32x4 (&acc)[2][2][4][2], const pg8::Unit& u, int wr, int wc, int fr, int fq) const {
;     ...
;                 f32x4 pa[2][2], pb[2][2]; float rs[2];
; #pragma unroll
;                 for (int mm = 0; mm < 2; ++mm) { const int row = row0 + ai * 128 + (2 * mh + mm) * 16; rs[mm] = sh[row] * alpha;
; #pragma unroll
;                     for (int bj = 0; bj < 2; ++bj) { const size_t off = (size_t)row * DM + col0 + bj * 128; pa[mm][bj] = *(const f32x4*)(res + off); pb[mm][bj] = *(const f32x4*)(res + off + 4); } }
; #pragma unroll
;                 for (int mm = 0; mm < 2; ++mm) {
;                     const int m = 2 * mh + mm, row = row0 + ai * 128 + m * 16; float ss = 0.f;
; #pragma unroll
;                     for (int bj = 0; bj < 2; ++bj) {
;                         const size_t off = (size_t)row * DM + col0 + bj * 128; f32x4 v0, v1;
; #pragma unroll
;                         for (int e = 0; e < 4; ++e) { v0[e] = pa[mm][bj][e] + (float)acc[ai][bj][m][0][e] * rs[mm] * s0[bj][e]; v1[e] = pb[mm][bj][e] + (float)acc[ai][bj][m][1][e] * rs[mm] * s1[bj][e]; }
;                         if (out) { *(f32x4*)(out + off) = v0; *(f32x4*)(out + off + 4) = v1; }
;                         if (ob) { u32x4 w; w.x = cvt_pk_bf16(v0[0], v0[1]); w.y = cvt_pk_bf16(v0[2], v0[3]); w.z = cvt_pk_bf16(v1[0], v1[1]); w.w = cvt_pk_bf16(v1[2], v1[3]); *(u32x4*)(ob + blk_off(row, col0 + bj * 128, KT4)) = w; }
;                         ss += (v0[0] * v0[0] + v0[1] * v0[1]) + (v0[2] * v0[2] + v0[3] * v0[3]) + (v1[0] * v1[0] + v1[1] * v1[1]) + (v1[2] * v1[2] + v1[3] * v1[3]);
;                     }
;                     ss += __shfl_xor(ss, 16); ss += __shfl_xor(ss, 32);
;                     if (fq == 0 && racc) atomicAdd(racc + row, (u64)(ss * 4294967296.0f));
.LBB0_1396:
	v_lshl_add_u32 v176, s45, 8, v1
	v_lshl_or_b32 v206, s46, 8, v179
	v_cvt_f32_i32_e32 v217, v134
	v_ashrrev_i32_e32 v177, 31, v176
	v_lshl_add_u64 v[66:67], v[176:177], 2, s[8:9]
	v_ashrrev_i32_e32 v207, 31, v206
	global_load_dword v185, v[66:67], off
	v_lshlrev_b64 v[66:67], 2, v[206:207]
	v_lshl_add_u64 v[70:71], s[10:11], 0, v[66:67]
	global_load_dwordx4 v[74:77], v[70:71], off offset:16 nt
	global_load_dwordx4 v[78:81], v[70:71], off nt
	v_lshlrev_b64 v[68:69], 14, v[176:177]
	v_lshl_add_u64 v[174:175], v[154:155], 0, v[66:67]
	v_lshl_add_u64 v[146:147], v[174:175], 0, v[68:69]
	global_load_dwordx4 v[186:189], v[146:147], off nt
	global_load_dwordx4 v[190:193], v[146:147], off offset:16 nt
	global_load_dwordx4 v[66:69], v[70:71], off offset:528 nt
	s_nop 0
	global_load_dwordx4 v[70:73], v[70:71], off offset:512 nt
	s_nop 0
	global_load_dwordx4 v[194:197], v[146:147], off offset:512 nt
	global_load_dwordx4 v[198:201], v[146:147], off offset:528 nt
	v_add_u32_e32 v134, 16, v176
	v_cvt_f32_i32_e32 v214, v140
	v_cvt_f32_i32_e32 v219, v135
	v_lshlrev_b32_e32 v140, 7, v176
	v_ashrrev_i32_e32 v135, 31, v134
	v_cvt_f32_i32_e32 v205, v138
	v_cvt_f32_i32_e32 v212, v139
	v_cvt_f32_i32_e32 v216, v141
	v_and_b32_e32 v138, 63, v206
	v_ashrrev_i32_e32 v139, 2, v176
	v_and_b32_e32 v208, 0x7f80, v140
	v_lshlrev_b64 v[140:141], 14, v[134:135]
	v_cvt_f32_i32_e32 v204, v142
	v_cvt_f32_i32_e32 v207, v143
	v_and_b32_e32 v220, 0xffffffc0, v139
	v_lshlrev_b32_e32 v164, 1, v138
	v_lshl_add_u64 v[138:139], v[134:135], 2, s[8:9]
	v_lshl_add_u64 v[142:143], v[174:175], 0, v[140:141]
	v_cvt_f32_i32_e32 v213, v144
	v_cvt_f32_i32_e32 v215, v145
	global_load_dword v184, v[138:139], off
	global_load_dwordx4 v[146:149], v[142:143], off offset:16 nt
	global_load_dwordx4 v[150:153], v[142:143], off nt
	s_nop 0
	global_load_dwordx4 v[138:141], v[142:143], off offset:528 nt
	s_nop 0
	global_load_dwordx4 v[142:145], v[142:143], off offset:512 nt
	v_cvt_f32_i32_e32 v218, v130
	v_ashrrev_i32_e32 v130, 6, v206
	v_add_u32_e32 v202, v220, v130
	v_ashrrev_i32_e32 v203, 31, v202
	v_lshlrev_b64 v[202:203], 15, v[202:203]
	v_mov_b32_e32 v209, v165
	v_lshl_add_u64 v[202:203], s[72:73], 0, v[202:203]
	v_lshl_add_u64 v[202:203], v[202:203], 0, v[208:209]
	v_lshl_add_u64 v[210:211], v[202:203], 0, v[164:165]
	v_cvt_f32_i32_e32 v137, v137
	v_cvt_f32_i32_e32 v131, v131
	v_cvt_f32_i32_e32 v136, v136
	v_cvt_f32_i32_e32 v132, v132
	v_cvt_f32_i32_e32 v133, v133
	s_waitcnt vmcnt(0)
	v_mul_f32_e32 v185, 0.5, v185
	v_mul_f32_e32 v202, v185, v204
	v_mul_f32_e32 v204, v185, v207
	v_mul_f32_e32 v207, v185, v213
	v_mul_f32_e32 v213, v185, v215
	v_mul_f32_e32 v203, v185, v205
	v_mul_f32_e32 v205, v185, v212
	v_fma_f32 v187, v79, v204, v187
	v_fmac_f32_e32 v189, v81, v213
	v_mul_f32_e32 v212, v185, v214
	v_mul_f32_e32 v214, v185, v216
	v_fma_f32 v186, v78, v202, v186
	v_fma_f32 v190, v74, v203, v190
	v_fma_f32 v191, v75, v205, v191
	v_fma_f32 v188, v80, v207, v188
	v_cvt_pk_bf16_f32 v202, v186, v187
	v_cvt_pk_bf16_f32 v203, v188, v189
	v_mul_f32_e32 v187, v187, v187
	v_mul_f32_e32 v189, v189, v189
	v_fmac_f32_e32 v193, v77, v214
	v_cvt_pk_bf16_f32 v204, v190, v191
	v_mul_f32_e32 v191, v191, v191
	v_fmac_f32_e32 v187, v186, v186
	v_fmac_f32_e32 v189, v188, v188
	v_fma_f32 v192, v76, v212, v192
	v_cvt_pk_bf16_f32 v205, v192, v193
	v_mul_f32_e32 v193, v193, v193
	v_fmac_f32_e32 v191, v190, v190
	v_add_f32_e32 v186, v187, v189
	v_fmac_f32_e32 v193, v192, v192
	v_add_f32_e32 v186, v191, v186
	v_add_f32_e32 v190, v193, v186
	v_mul_f32_e32 v186, v185, v219
	v_mul_f32_e32 v137, v185, v137
	v_mul_f32_e32 v215, v185, v217
	v_fma_f32 v191, v71, v186, v195
	v_mul_f32_e32 v131, v185, v131
	v_mul_f32_e32 v136, v185, v136
	v_fmac_f32_e32 v197, v73, v137
	v_mul_f32_e32 v216, v185, v218
	v_fma_f32 v194, v70, v215, v194
	v_fma_f32 v131, v67, v131, v199
	v_fma_f32 v136, v72, v136, v196
	v_mul_f32_e32 v132, v185, v132
	v_mul_f32_e32 v133, v185, v133
	v_mul_f32_e32 v137, v191, v191
	v_mul_f32_e32 v185, v197, v197
	v_fma_f32 v198, v66, v216, v198
	global_store_dwordx4 v[210:211], v[202:205], off
	v_cvt_pk_bf16_f32 v186, v194, v191
	v_cvt_pk_bf16_f32 v187, v136, v197
	v_cvt_pk_bf16_f32 v188, v198, v131
	v_fmac_f32_e32 v137, v194, v194
	v_fmac_f32_e32 v185, v136, v136
	v_mul_f32_e32 v131, v131, v131
	v_fmac_f32_e32 v201, v69, v133
	v_add_f32_e32 v136, v137, v185
	v_fmac_f32_e32 v131, v198, v198
	v_fma_f32 v132, v68, v132, v200
	v_add_f32_e32 v131, v136, v131
	v_mul_f32_e32 v136, v201, v201
	v_fmac_f32_e32 v136, v132, v132
	v_cvt_pk_bf16_f32 v189, v132, v201
	v_add_f32_e32 v131, v136, v131
	v_and_b32_e32 v132, 64, v183
	v_add_f32_e32 v185, v190, v131
	v_xor_b32_e32 v131, 16, v183
	v_add_u32_e32 v192, 64, v132
	v_cmp_lt_i32_e32 vcc, v131, v192
	v_add_u32_e32 v133, 0x80, v206
	s_nop 0
	v_cndmask_b32_e32 v131, v183, v131, vcc
	v_lshlrev_b32_e32 v132, 2, v131
	ds_bpermute_b32 v193, v132, v185
	v_ashrrev_i32_e32 v131, 6, v133
	v_xor_b32_e32 v133, 32, v183
	v_add_u32_e32 v136, v131, v220
	v_cmp_lt_i32_e32 vcc, v133, v192
	v_ashrrev_i32_e32 v137, 31, v136
	v_lshlrev_b64 v[190:191], 15, v[136:137]
	v_cndmask_b32_e32 v133, v183, v133, vcc
	s_waitcnt lgkmcnt(0)
	v_add_f32_e32 v136, v185, v193
	v_lshlrev_b32_e32 v133, 2, v133
	ds_bpermute_b32 v137, v133, v136
	v_lshl_add_u64 v[190:191], s[72:73], 0, v[190:191]
	v_lshl_add_u64 v[190:191], v[190:191], 0, v[208:209]
	v_lshl_add_u64 v[190:191], v[190:191], 0, v[164:165]
	global_store_dwordx4 v[190:191], v[186:189], off
	s_and_saveexec_b64 s[18:19], s[2:3]
	s_cbranch_execz .LBB0_1398
	s_waitcnt lgkmcnt(0)
	v_add_f32_e32 v136, v136, v137
	v_mul_f32_e32 v136, 0x4f800000, v136
	v_trunc_f32_e32 v136, v136
	v_mul_f32_e32 v137, 0x2f800000, v136
	v_floor_f32_e32 v137, v137
	v_fmac_f32_e32 v136, 0xcf800000, v137
	v_cvt_u32_f32_e32 v136, v136
	v_cvt_u32_f32_e32 v137, v137
	v_lshl_add_u64 v[186:187], v[176:177], 3, s[12:13]
	global_atomic_add_x2 v[186:187], v[136:137], off

; __host__ __device__ __forceinline__ size_t blk_off(int r, int k, int KT) { return ((size_t)((r >> 8) * KT + (k >> 6)) * 256 + (size_t)(r & 255)) * 64 + (size_t)(k & 63); }
; __device__ __forceinline__ unsigned cvt_pk_bf16(float lo, float hi) { unsigned r; asm volatile("v_cvt_pk_bf16_f32 %0, %1, %2" : "=v"(r) : "v"(lo), "v"(hi)); return r; }
;     __device__ __forceinline__ void operator()(const i32x4 (&acc)[2][2][4][2], const pg8::Unit& u, int wr, int wc, int fr, int fq) const {
;     ...
;                 f32x4 pa[2][2], pb[2][2]; float rs[2];
; #pragma unroll
;                 for (int mm = 0; mm < 2; ++mm) { const int row = row0 + ai * 128 + (2 * mh + mm) * 16; rs[mm] = sh[row] * alpha;
; #pragma unroll
;                     for (int bj = 0; bj < 2; ++bj) { const size_t off = (size_t)row * DM + col0 + bj * 128; pa[mm][bj] = *(const f32x4*)(res + off); pb[mm][bj] = *(const f32x4*)(res + off + 4); } }
; #pragma unroll
;                 for (int mm = 0; mm < 2; ++mm) {
;                     const int m = 2 * mh + mm, row = row0 + ai * 128 + m * 16; float ss = 0.f;
; #pragma unroll
;                     for (int bj = 0; bj < 2; ++bj) {
;                         const size_t off = (size_t)row * DM + col0 + bj * 128; f32x4 v0, v1;
; #pragma unroll
;                         for (int e = 0; e < 4; ++e) { v0[e] = pa[mm][bj][e] + (float)acc[ai][bj][m][0][e] * rs[mm] * s0[bj][e]; v1[e] = pb[mm][bj][e] + (float)acc[ai][bj][m][1][e] * rs[mm] * s1[bj][e]; }
;                         if (out) { *(f32x4*)(out + off) = v0; *(f32x4*)(out + off + 4) = v1; }
;                         if (ob) { u32x4 w; w.x = cvt_pk_bf16(v0[0], v0[1]); w.y = cvt_pk_bf16(v0[2], v0[3]); w.z = cvt_pk_bf16(v1[0], v1[1]); w.w = cvt_pk_bf16(v1[2], v1[3]); *(u32x4*)(ob + blk_off(row, col0 + bj * 128, KT4)) = w; }
;                         ss += (v0[0] * v0[0] + v0[1] * v0[1]) + (v0[2] * v0[2] + v0[3] * v0[3]) + (v1[0] * v1[0] + v1[1] * v1[1]) + (v1[2] * v1[2] + v1[3] * v1[3]);
;                     }
;                     ss += __shfl_xor(ss, 16); ss += __shfl_xor(ss, 32);
;                     if (fq == 0 && racc) atomicAdd(racc + row, (u64)(ss * 4294967296.0f));
.LBB0_1400:
	s_or_b64 exec, exec, s[18:19]
	v_add_u32_e32 v116, 32, v176
	v_ashrrev_i32_e32 v117, 31, v116
	s_waitcnt lgkmcnt(0)
	v_lshl_add_u64 v[114:115], v[116:117], 2, s[8:9]
	global_load_dword v119, v[114:115], off
	v_lshlrev_b64 v[114:115], 14, v[116:117]
	v_lshl_add_u64 v[114:115], v[174:175], 0, v[114:115]
	global_load_dwordx4 v[120:123], v[114:115], off nt
	global_load_dwordx4 v[124:127], v[114:115], off offset:16 nt
	global_load_dwordx4 v[134:137], v[114:115], off offset:512 nt
	global_load_dwordx4 v[138:141], v[114:115], off offset:528 nt
	v_add_u32_e32 v114, 48, v176
	v_ashrrev_i32_e32 v115, 31, v114
	v_cvt_f32_i32_e32 v177, v102
	v_cvt_f32_i32_e32 v185, v103
	v_cvt_f32_i32_e32 v188, v100
	v_cvt_f32_i32_e32 v190, v101
	v_ashrrev_i32_e32 v102, 2, v116
	v_lshlrev_b32_e32 v103, 7, v116
	v_lshlrev_b64 v[100:101], 14, v[114:115]
	v_cvt_f32_i32_e32 v184, v98
	v_cvt_f32_i32_e32 v186, v99
	v_lshl_add_u64 v[98:99], v[114:115], 2, s[8:9]
	v_and_b32_e32 v191, 0xffffffc0, v102
	v_and_b32_e32 v128, 0x7f80, v103
	v_lshl_add_u64 v[102:103], v[174:175], 0, v[100:101]
	v_cvt_f32_i32_e32 v144, v110
	v_cvt_f32_i32_e32 v145, v106
	v_cvt_f32_i32_e32 v148, v111
	v_cvt_f32_i32_e32 v149, v107
	v_cvt_f32_i32_e32 v150, v112
	v_cvt_f32_i32_e32 v151, v108
	v_cvt_f32_i32_e32 v152, v113
	v_cvt_f32_i32_e32 v153, v109
	v_cvt_f32_i32_e32 v187, v104
	v_cvt_f32_i32_e32 v189, v105
	global_load_dword v118, v[98:99], off
	global_load_dwordx4 v[106:109], v[102:103], off offset:16 nt
	global_load_dwordx4 v[110:113], v[102:103], off nt
	s_nop 0
	global_load_dwordx4 v[98:101], v[102:103], off offset:528 nt
	s_nop 0
	global_load_dwordx4 v[102:105], v[102:103], off offset:512 nt
	v_add_u32_e32 v142, v191, v130
	v_ashrrev_i32_e32 v143, 31, v142
	v_lshlrev_b64 v[142:143], 15, v[142:143]
	v_mov_b32_e32 v129, v165
	v_lshl_add_u64 v[142:143], s[72:73], 0, v[142:143]
	v_lshl_add_u64 v[142:143], v[142:143], 0, v[128:129]
	v_lshl_add_u64 v[146:147], v[142:143], 0, v[164:165]
	s_waitcnt vmcnt(9)
	v_mul_f32_e32 v119, 0.5, v119
	v_mul_f32_e32 v142, v119, v144
	v_mul_f32_e32 v144, v119, v148
	v_mul_f32_e32 v148, v119, v150
	v_mul_f32_e32 v150, v119, v152
	v_mul_f32_e32 v143, v119, v145
	v_mul_f32_e32 v145, v119, v149
	s_waitcnt vmcnt(8)
	v_fma_f32 v121, v79, v144, v121
	v_fmac_f32_e32 v123, v81, v150
	v_fma_f32 v120, v78, v142, v120
	s_waitcnt vmcnt(7)
	v_fma_f32 v124, v74, v143, v124
	v_fma_f32 v125, v75, v145, v125
	v_fma_f32 v122, v80, v148, v122
	v_cvt_pk_bf16_f32 v142, v120, v121
	v_cvt_pk_bf16_f32 v143, v122, v123
	v_mul_f32_e32 v121, v121, v121
	v_mul_f32_e32 v123, v123, v123
	v_mul_f32_e32 v152, v119, v177
	v_mul_f32_e32 v177, v119, v185
	v_cvt_pk_bf16_f32 v144, v124, v125
	v_mul_f32_e32 v125, v125, v125
	v_fmac_f32_e32 v121, v120, v120
	v_fmac_f32_e32 v123, v122, v122
	v_mul_f32_e32 v122, v119, v189
	v_mul_f32_e32 v149, v119, v151
	v_mul_f32_e32 v151, v119, v153
	v_mul_f32_e32 v153, v119, v184
	v_mul_f32_e32 v184, v119, v186
	v_mul_f32_e32 v185, v119, v187
	v_mul_f32_e32 v186, v119, v188
	s_waitcnt vmcnt(6)
	v_fma_f32 v135, v71, v177, v135
	v_fmac_f32_e32 v125, v124, v124
	v_add_f32_e32 v120, v121, v123
	v_fmac_f32_e32 v137, v73, v122
	v_mul_f32_e32 v119, v119, v190
	v_fma_f32 v134, v70, v152, v134
	v_fma_f32 v136, v72, v185, v136
	v_add_f32_e32 v120, v125, v120
	s_waitcnt vmcnt(5)
	v_fmac_f32_e32 v141, v69, v119
	v_mul_f32_e32 v119, v135, v135
	v_mul_f32_e32 v125, v137, v137
	v_fma_f32 v139, v67, v184, v139
	v_fmac_f32_e32 v119, v134, v134
	v_fmac_f32_e32 v125, v136, v136
	v_fma_f32 v138, v66, v153, v138
	v_add_f32_e32 v119, v119, v125
	v_mul_f32_e32 v125, v139, v139
	v_fmac_f32_e32 v127, v77, v151
	v_fmac_f32_e32 v125, v138, v138
	v_fma_f32 v126, v76, v149, v126
	v_cvt_pk_bf16_f32 v145, v126, v127
	v_mul_f32_e32 v127, v127, v127
	v_fma_f32 v121, v68, v186, v140
	v_add_f32_e32 v119, v119, v125
	v_mul_f32_e32 v125, v141, v141
	v_fmac_f32_e32 v127, v126, v126
	v_fmac_f32_e32 v125, v121, v121
	v_add_f32_e32 v120, v127, v120
	v_add_f32_e32 v119, v125, v119
	v_add_f32_e32 v119, v120, v119
	global_store_dwordx4 v[146:147], v[142:145], off
	v_cvt_pk_bf16_f32 v122, v134, v135
	ds_bpermute_b32 v134, v132, v119
	v_add_u32_e32 v120, v191, v131
	v_cvt_pk_bf16_f32 v123, v136, v137
	v_cvt_pk_bf16_f32 v124, v138, v139
	v_cvt_pk_bf16_f32 v125, v121, v141
	v_ashrrev_i32_e32 v121, 31, v120
	s_waitcnt lgkmcnt(0)
	v_add_f32_e32 v119, v119, v134
	v_lshlrev_b64 v[126:127], 15, v[120:121]
	ds_bpermute_b32 v120, v133, v119
	v_lshl_add_u64 v[126:127], s[72:73], 0, v[126:127]
	v_lshl_add_u64 v[126:127], v[126:127], 0, v[128:129]
	v_lshl_add_u64 v[126:127], v[126:127], 0, v[164:165]
	global_store_dwordx4 v[126:127], v[122:125], off
	s_and_saveexec_b64 s[18:19], s[2:3]
	s_cbranch_execz .LBB0_1402
	s_waitcnt lgkmcnt(0)
	v_add_f32_e32 v119, v119, v120
	v_mul_f32_e32 v119, 0x4f800000, v119
	v_trunc_f32_e32 v119, v119
	v_mul_f32_e32 v120, 0x2f800000, v119
	v_floor_f32_e32 v121, v120
	v_fmac_f32_e32 v119, 0xcf800000, v121
	v_cvt_u32_f32_e32 v120, v119
	v_cvt_u32_f32_e32 v121, v121
	v_lshl_add_u64 v[116:117], v[116:117], 3, s[12:13]
	global_atomic_add_x2 v[116:117], v[120:121], off

; __host__ __device__ __forceinline__ size_t blk_off(int r, int k, int KT) { return ((size_t)((r >> 8) * KT + (k >> 6)) * 256 + (size_t)(r & 255)) * 64 + (size_t)(k & 63); }
; __device__ __forceinline__ unsigned cvt_pk_bf16(float lo, float hi) { unsigned r; asm volatile("v_cvt_pk_bf16_f32 %0, %1, %2" : "=v"(r) : "v"(lo), "v"(hi)); return r; }
;     __device__ __forceinline__ void operator()(const i32x4 (&acc)[2][2][4][2], const pg8::Unit& u, int wr, int wc, int fr, int fq) const {
;     ...
;                 f32x4 pa[2][2], pb[2][2]; float rs[2];
; #pragma unroll
;                 for (int mm = 0; mm < 2; ++mm) { const int row = row0 + ai * 128 + (2 * mh + mm) * 16; rs[mm] = sh[row] * alpha;
; #pragma unroll
;                     for (int bj = 0; bj < 2; ++bj) { const size_t off = (size_t)row * DM + col0 + bj * 128; pa[mm][bj] = *(const f32x4*)(res + off); pb[mm][bj] = *(const f32x4*)(res + off + 4); } }
; #pragma unroll
;                 for (int mm = 0; mm < 2; ++mm) {
;                     const int m = 2 * mh + mm, row = row0 + ai * 128 + m * 16; float ss = 0.f;
; #pragma unroll
;                     for (int bj = 0; bj < 2; ++bj) {
;                         const size_t off = (size_t)row * DM + col0 + bj * 128; f32x4 v0, v1;
; #pragma unroll
;                         for (int e = 0; e < 4; ++e) { v0[e] = pa[mm][bj][e] + (float)acc[ai][bj][m][0][e] * rs[mm] * s0[bj][e]; v1[e] = pb[mm][bj][e] + (float)acc[ai][bj][m][1][e] * rs[mm] * s1[bj][e]; }
;                         if (out) { *(f32x4*)(out + off) = v0; *(f32x4*)(out + off + 4) = v1; }
;                         if (ob) { u32x4 w; w.x = cvt_pk_bf16(v0[0], v0[1]); w.y = cvt_pk_bf16(v0[2], v0[3]); w.z = cvt_pk_bf16(v1[0], v1[1]); w.w = cvt_pk_bf16(v1[2], v1[3]); *(u32x4*)(ob + blk_off(row, col0 + bj * 128, KT4)) = w; }
;                         ss += (v0[0] * v0[0] + v0[1] * v0[1]) + (v0[2] * v0[2] + v0[3] * v0[3]) + (v1[0] * v1[0] + v1[1] * v1[1]) + (v1[2] * v1[2] + v1[3] * v1[3]);
;                     }
;                     ss += __shfl_xor(ss, 16); ss += __shfl_xor(ss, 32);
;                     if (fq == 0 && racc) atomicAdd(racc + row, (u64)(ss * 4294967296.0f));
.LBB0_1404:
	s_or_b64 exec, exec, s[18:19]
	v_add_u32_e32 v84, 0x80, v176
	v_ashrrev_i32_e32 v85, 31, v84
	s_waitcnt lgkmcnt(0)
	v_lshl_add_u64 v[82:83], v[84:85], 2, s[8:9]
	global_load_dword v87, v[82:83], off
	v_lshlrev_b64 v[82:83], 14, v[84:85]
	v_lshl_add_u64 v[82:83], v[174:175], 0, v[82:83]
	global_load_dwordx4 v[88:91], v[82:83], off nt
	global_load_dwordx4 v[92:95], v[82:83], off offset:16 nt
	global_load_dwordx4 v[96:99], v[82:83], off offset:512 nt
	global_load_dwordx4 v[100:103], v[82:83], off offset:528 nt
	v_add_u32_e32 v82, 0x90, v176
	v_ashrrev_i32_e32 v83, 31, v82
	v_cvt_f32_i32_e32 v118, v54
	v_cvt_f32_i32_e32 v120, v55
	v_cvt_f32_i32_e32 v123, v52
	v_cvt_f32_i32_e32 v125, v53
	v_ashrrev_i32_e32 v54, 2, v84
	v_lshlrev_b32_e32 v55, 7, v84
	v_lshlrev_b64 v[52:53], 14, v[82:83]
	v_cvt_f32_i32_e32 v119, v50
	v_cvt_f32_i32_e32 v121, v51
	v_lshl_add_u64 v[50:51], v[82:83], 2, s[8:9]
	v_and_b32_e32 v126, 0xffffffc0, v54
	v_and_b32_e32 v108, 0x7f80, v55
	v_lshl_add_u64 v[54:55], v[174:175], 0, v[52:53]
	v_cvt_f32_i32_e32 v106, v62
	v_cvt_f32_i32_e32 v107, v58
	v_cvt_f32_i32_e32 v112, v63
	v_cvt_f32_i32_e32 v113, v59
	v_cvt_f32_i32_e32 v114, v64
	v_cvt_f32_i32_e32 v115, v60
	v_cvt_f32_i32_e32 v116, v65
	v_cvt_f32_i32_e32 v117, v61
	v_cvt_f32_i32_e32 v122, v56
	v_cvt_f32_i32_e32 v124, v57
	global_load_dword v86, v[50:51], off
	global_load_dwordx4 v[58:61], v[54:55], off offset:16 nt
	global_load_dwordx4 v[62:65], v[54:55], off nt
	s_nop 0
	global_load_dwordx4 v[50:53], v[54:55], off offset:528 nt
	s_nop 0
	global_load_dwordx4 v[54:57], v[54:55], off offset:512 nt
	v_add_u32_e32 v104, v126, v130
	v_ashrrev_i32_e32 v105, 31, v104
	v_lshlrev_b64 v[104:105], 15, v[104:105]
	v_mov_b32_e32 v109, v165
	v_lshl_add_u64 v[104:105], s[72:73], 0, v[104:105]
	v_lshl_add_u64 v[104:105], v[104:105], 0, v[108:109]
	v_lshl_add_u64 v[110:111], v[104:105], 0, v[164:165]
	s_waitcnt vmcnt(9)
	v_mul_f32_e32 v87, 0.5, v87
	v_mul_f32_e32 v104, v87, v106
	v_mul_f32_e32 v106, v87, v112
	v_mul_f32_e32 v112, v87, v114
	v_mul_f32_e32 v114, v87, v116
	v_mul_f32_e32 v105, v87, v107
	v_mul_f32_e32 v107, v87, v113
	s_waitcnt vmcnt(8)
	v_fma_f32 v89, v79, v106, v89
	v_fmac_f32_e32 v91, v81, v114
	v_fma_f32 v88, v78, v104, v88
	s_waitcnt vmcnt(7)
	v_fma_f32 v92, v74, v105, v92
	v_fma_f32 v93, v75, v107, v93
	v_fma_f32 v90, v80, v112, v90
	v_cvt_pk_bf16_f32 v104, v88, v89
	v_cvt_pk_bf16_f32 v105, v90, v91
	v_mul_f32_e32 v89, v89, v89
	v_mul_f32_e32 v91, v91, v91
	v_mul_f32_e32 v116, v87, v118
	v_mul_f32_e32 v118, v87, v120
	v_cvt_pk_bf16_f32 v106, v92, v93
	v_mul_f32_e32 v93, v93, v93
	v_fmac_f32_e32 v89, v88, v88
	v_fmac_f32_e32 v91, v90, v90
	v_mul_f32_e32 v90, v87, v124
	v_mul_f32_e32 v113, v87, v115
	v_mul_f32_e32 v115, v87, v117
	v_mul_f32_e32 v117, v87, v119
	v_mul_f32_e32 v119, v87, v121
	v_mul_f32_e32 v120, v87, v122
	v_mul_f32_e32 v121, v87, v123
	s_waitcnt vmcnt(6)
	v_fma_f32 v97, v71, v118, v97
	v_fmac_f32_e32 v93, v92, v92
	v_add_f32_e32 v88, v89, v91
	v_fmac_f32_e32 v99, v73, v90
	v_mul_f32_e32 v87, v87, v125
	v_fma_f32 v96, v70, v116, v96
	v_fma_f32 v98, v72, v120, v98
	v_add_f32_e32 v88, v93, v88
	s_waitcnt vmcnt(5)
	v_fmac_f32_e32 v103, v69, v87
	v_mul_f32_e32 v87, v97, v97
	v_mul_f32_e32 v93, v99, v99
	v_fma_f32 v101, v67, v119, v101
	v_fmac_f32_e32 v87, v96, v96
	v_fmac_f32_e32 v93, v98, v98
	v_fma_f32 v100, v66, v117, v100
	v_add_f32_e32 v87, v87, v93
	v_mul_f32_e32 v93, v101, v101
	v_fmac_f32_e32 v95, v77, v115
	v_fmac_f32_e32 v93, v100, v100
	v_fma_f32 v94, v76, v113, v94
	v_cvt_pk_bf16_f32 v107, v94, v95
	v_mul_f32_e32 v95, v95, v95
	v_fma_f32 v89, v68, v121, v102
	v_add_f32_e32 v87, v87, v93
	v_mul_f32_e32 v93, v103, v103
	v_fmac_f32_e32 v95, v94, v94
	v_fmac_f32_e32 v93, v89, v89
	v_add_f32_e32 v88, v95, v88
	v_add_f32_e32 v87, v93, v87
	v_add_f32_e32 v87, v88, v87
	global_store_dwordx4 v[110:111], v[104:107], off
	v_cvt_pk_bf16_f32 v90, v96, v97
	ds_bpermute_b32 v96, v132, v87
	v_add_u32_e32 v88, v126, v131
	v_cvt_pk_bf16_f32 v91, v98, v99
	v_cvt_pk_bf16_f32 v92, v100, v101
	v_cvt_pk_bf16_f32 v93, v89, v103
	v_ashrrev_i32_e32 v89, 31, v88
	s_waitcnt lgkmcnt(0)
	v_add_f32_e32 v87, v87, v96
	v_lshlrev_b64 v[94:95], 15, v[88:89]
	ds_bpermute_b32 v88, v133, v87
	v_lshl_add_u64 v[94:95], s[72:73], 0, v[94:95]
	v_lshl_add_u64 v[94:95], v[94:95], 0, v[108:109]
	v_lshl_add_u64 v[94:95], v[94:95], 0, v[164:165]
	global_store_dwordx4 v[94:95], v[90:93], off
	s_and_saveexec_b64 s[18:19], s[2:3]
	s_cbranch_execz .LBB0_1406
	s_waitcnt lgkmcnt(0)
	v_add_f32_e32 v87, v87, v88
	v_mul_f32_e32 v87, 0x4f800000, v87
	v_trunc_f32_e32 v87, v87
	v_mul_f32_e32 v88, 0x2f800000, v87
	v_floor_f32_e32 v89, v88
	v_fmac_f32_e32 v87, 0xcf800000, v89
	v_cvt_u32_f32_e32 v88, v87
	v_cvt_u32_f32_e32 v89, v89
	v_lshl_add_u64 v[84:85], v[84:85], 3, s[12:13]
	global_atomic_add_x2 v[84:85], v[88:89], off

; __host__ __device__ __forceinline__ size_t blk_off(int r, int k, int KT) { return ((size_t)((r >> 8) * KT + (k >> 6)) * 256 + (size_t)(r & 255)) * 64 + (size_t)(k & 63); }
; __device__ __forceinline__ unsigned cvt_pk_bf16(float lo, float hi) { unsigned r; asm volatile("v_cvt_pk_bf16_f32 %0, %1, %2" : "=v"(r) : "v"(lo), "v"(hi)); return r; }
;     __device__ __forceinline__ void operator()(const i32x4 (&acc)[2][2][4][2], const pg8::Unit& u, int wr, int wc, int fr, int fq) const {
;     ...
;                 f32x4 pa[2][2], pb[2][2]; float rs[2];
; #pragma unroll
;                 for (int mm = 0; mm < 2; ++mm) { const int row = row0 + ai * 128 + (2 * mh + mm) * 16; rs[mm] = sh[row] * alpha;
; #pragma unroll
;                     for (int bj = 0; bj < 2; ++bj) { const size_t off = (size_t)row * DM + col0 + bj * 128; pa[mm][bj] = *(const f32x4*)(res + off); pb[mm][bj] = *(const f32x4*)(res + off + 4); } }
; #pragma unroll
;                 for (int mm = 0; mm < 2; ++mm) {
;                     const int m = 2 * mh + mm, row = row0 + ai * 128 + m * 16; float ss = 0.f;
; #pragma unroll
;                     for (int bj = 0; bj < 2; ++bj) {
;                         const size_t off = (size_t)row * DM + col0 + bj * 128; f32x4 v0, v1;
; #pragma unroll
;                         for (int e = 0; e < 4; ++e) { v0[e] = pa[mm][bj][e] + (float)acc[ai][bj][m][0][e] * rs[mm] * s0[bj][e]; v1[e] = pb[mm][bj][e] + (float)acc[ai][bj][m][1][e] * rs[mm] * s1[bj][e]; }
;                         if (out) { *(f32x4*)(out + off) = v0; *(f32x4*)(out + off + 4) = v1; }
;                         if (ob) { u32x4 w; w.x = cvt_pk_bf16(v0[0], v0[1]); w.y = cvt_pk_bf16(v0[2], v0[3]); w.z = cvt_pk_bf16(v1[0], v1[1]); w.w = cvt_pk_bf16(v1[2], v1[3]); *(u32x4*)(ob + blk_off(row, col0 + bj * 128, KT4)) = w; }
;                         ss += (v0[0] * v0[0] + v0[1] * v0[1]) + (v0[2] * v0[2] + v0[3] * v0[3]) + (v1[0] * v1[0] + v1[1] * v1[1]) + (v1[2] * v1[2] + v1[3] * v1[3]);
;                     }
;                     ss += __shfl_xor(ss, 16); ss += __shfl_xor(ss, 32);
;                     if (fq == 0 && racc) atomicAdd(racc + row, (u64)(ss * 4294967296.0f));
.LBB0_1408:
	s_or_b64 exec, exec, s[18:19]
	v_add_u32_e32 v36, 0xa0, v176
	v_ashrrev_i32_e32 v37, 31, v36
	s_waitcnt lgkmcnt(0)
	v_lshl_add_u64 v[34:35], v[36:37], 2, s[8:9]
	global_load_dword v39, v[34:35], off
	v_lshlrev_b64 v[34:35], 14, v[36:37]
	v_lshl_add_u64 v[34:35], v[174:175], 0, v[34:35]
	global_load_dwordx4 v[40:43], v[34:35], off nt
	global_load_dwordx4 v[44:47], v[34:35], off offset:16 nt
	global_load_dwordx4 v[48:51], v[34:35], off offset:512 nt
	global_load_dwordx4 v[52:55], v[34:35], off offset:528 nt
	v_add_u32_e32 v34, 0xb0, v176
	v_ashrrev_i32_e32 v35, 31, v34
	v_cvt_f32_i32_e32 v86, v22
	v_cvt_f32_i32_e32 v88, v23
	v_cvt_f32_i32_e32 v91, v20
	v_cvt_f32_i32_e32 v93, v21
	v_ashrrev_i32_e32 v22, 2, v36
	v_lshlrev_b32_e32 v23, 7, v36
	v_lshlrev_b64 v[20:21], 14, v[34:35]
	v_cvt_f32_i32_e32 v87, v18
	v_cvt_f32_i32_e32 v89, v19
	v_lshl_add_u64 v[18:19], v[34:35], 2, s[8:9]
	v_and_b32_e32 v94, 0xffffffc0, v22
	v_and_b32_e32 v60, 0x7f80, v23
	v_lshl_add_u64 v[22:23], v[174:175], 0, v[20:21]
	v_cvt_f32_i32_e32 v58, v30
	v_cvt_f32_i32_e32 v59, v26
	v_cvt_f32_i32_e32 v64, v31
	v_cvt_f32_i32_e32 v65, v27
	v_cvt_f32_i32_e32 v82, v32
	v_cvt_f32_i32_e32 v83, v28
	v_cvt_f32_i32_e32 v84, v33
	v_cvt_f32_i32_e32 v85, v29
	v_cvt_f32_i32_e32 v90, v24
	v_cvt_f32_i32_e32 v92, v25
	global_load_dword v38, v[18:19], off
	global_load_dwordx4 v[26:29], v[22:23], off offset:16 nt
	global_load_dwordx4 v[30:33], v[22:23], off nt
	s_nop 0
	global_load_dwordx4 v[18:21], v[22:23], off offset:528 nt
	s_nop 0
	global_load_dwordx4 v[22:25], v[22:23], off offset:512 nt
	v_add_u32_e32 v56, v94, v130
	v_ashrrev_i32_e32 v57, 31, v56
	v_lshlrev_b64 v[56:57], 15, v[56:57]
	v_mov_b32_e32 v61, v165
	v_lshl_add_u64 v[56:57], s[72:73], 0, v[56:57]
	v_lshl_add_u64 v[56:57], v[56:57], 0, v[60:61]
	v_lshl_add_u64 v[62:63], v[56:57], 0, v[164:165]
	s_waitcnt vmcnt(9)
	v_mul_f32_e32 v39, 0.5, v39
	v_mul_f32_e32 v56, v39, v58
	v_mul_f32_e32 v58, v39, v64
	v_mul_f32_e32 v64, v39, v82
	v_mul_f32_e32 v82, v39, v84
	v_mul_f32_e32 v57, v39, v59
	v_mul_f32_e32 v59, v39, v65
	s_waitcnt vmcnt(8)
	v_fma_f32 v41, v79, v58, v41
	v_fmac_f32_e32 v43, v81, v82
	v_fma_f32 v40, v78, v56, v40
	s_waitcnt vmcnt(7)
	v_fma_f32 v44, v74, v57, v44
	v_fma_f32 v45, v75, v59, v45
	v_fma_f32 v42, v80, v64, v42
	v_cvt_pk_bf16_f32 v56, v40, v41
	v_cvt_pk_bf16_f32 v57, v42, v43
	v_mul_f32_e32 v41, v41, v41
	v_mul_f32_e32 v43, v43, v43
	v_mul_f32_e32 v84, v39, v86
	v_mul_f32_e32 v86, v39, v88
	v_cvt_pk_bf16_f32 v58, v44, v45
	v_mul_f32_e32 v45, v45, v45
	v_fmac_f32_e32 v41, v40, v40
	v_fmac_f32_e32 v43, v42, v42
	v_mul_f32_e32 v42, v39, v92
	v_mul_f32_e32 v65, v39, v83
	v_mul_f32_e32 v83, v39, v85
	v_mul_f32_e32 v85, v39, v87
	v_mul_f32_e32 v87, v39, v89
	v_mul_f32_e32 v88, v39, v90
	v_mul_f32_e32 v89, v39, v91
	s_waitcnt vmcnt(6)
	v_fma_f32 v49, v71, v86, v49
	v_fmac_f32_e32 v45, v44, v44
	v_add_f32_e32 v40, v41, v43
	v_fmac_f32_e32 v51, v73, v42
	v_mul_f32_e32 v39, v39, v93
	v_fma_f32 v48, v70, v84, v48
	v_fma_f32 v50, v72, v88, v50
	v_add_f32_e32 v40, v45, v40
	s_waitcnt vmcnt(5)
	v_fmac_f32_e32 v55, v69, v39
	v_mul_f32_e32 v39, v49, v49
	v_mul_f32_e32 v45, v51, v51
	v_fma_f32 v53, v67, v87, v53
	v_fmac_f32_e32 v39, v48, v48
	v_fmac_f32_e32 v45, v50, v50
	v_fma_f32 v52, v66, v85, v52
	v_add_f32_e32 v39, v39, v45
	v_mul_f32_e32 v45, v53, v53
	v_fmac_f32_e32 v47, v77, v83
	v_fmac_f32_e32 v45, v52, v52
	v_fma_f32 v46, v76, v65, v46
	v_cvt_pk_bf16_f32 v59, v46, v47
	v_mul_f32_e32 v47, v47, v47
	v_fma_f32 v41, v68, v89, v54
	v_add_f32_e32 v39, v39, v45
	v_mul_f32_e32 v45, v55, v55
	v_fmac_f32_e32 v47, v46, v46
	v_fmac_f32_e32 v45, v41, v41
	v_add_f32_e32 v40, v47, v40
	v_add_f32_e32 v39, v45, v39
	v_add_f32_e32 v39, v40, v39
	global_store_dwordx4 v[62:63], v[56:59], off
	v_cvt_pk_bf16_f32 v42, v48, v49
	ds_bpermute_b32 v48, v132, v39
	v_add_u32_e32 v40, v94, v131
	v_cvt_pk_bf16_f32 v43, v50, v51
	v_cvt_pk_bf16_f32 v44, v52, v53
	v_cvt_pk_bf16_f32 v45, v41, v55
	v_ashrrev_i32_e32 v41, 31, v40
	s_waitcnt lgkmcnt(0)
	v_add_f32_e32 v39, v39, v48
	v_lshlrev_b64 v[46:47], 15, v[40:41]
	ds_bpermute_b32 v40, v133, v39
	v_lshl_add_u64 v[46:47], s[72:73], 0, v[46:47]
	v_lshl_add_u64 v[46:47], v[46:47], 0, v[60:61]
	v_lshl_add_u64 v[46:47], v[46:47], 0, v[164:165]
	global_store_dwordx4 v[46:47], v[42:45], off
	s_and_saveexec_b64 s[18:19], s[2:3]
	s_cbranch_execz .LBB0_1410
	s_waitcnt lgkmcnt(0)
	v_add_f32_e32 v39, v39, v40
	v_mul_f32_e32 v39, 0x4f800000, v39
	v_trunc_f32_e32 v39, v39
	v_mul_f32_e32 v40, 0x2f800000, v39
	v_floor_f32_e32 v41, v40
	v_fmac_f32_e32 v39, 0xcf800000, v41
	v_cvt_u32_f32_e32 v40, v39
	v_cvt_u32_f32_e32 v41, v41
	v_lshl_add_u64 v[36:37], v[36:37], 3, s[12:13]
	global_atomic_add_x2 v[36:37], v[40:41], off

; __host__ __device__ __forceinline__ size_t blk_off(int r, int k, int KT) { return ((size_t)((r >> 8) * KT + (k >> 6)) * 256 + (size_t)(r & 255)) * 64 + (size_t)(k & 63); }
; __device__ __forceinline__ unsigned cvt_pk_bf16(float lo, float hi) { unsigned r; asm volatile("v_cvt_pk_bf16_f32 %0, %1, %2" : "=v"(r) : "v"(lo), "v"(hi)); return r; }
;     __device__ __forceinline__ void operator()(const i32x4 (&acc)[2][2][4][2], const pg8::Unit& u, int wr, int wc, int fr, int fq) const {
;     ...
;                 f32x4 pa[2][2], pb[2][2]; float rs[2];
; #pragma unroll
;                 for (int mm = 0; mm < 2; ++mm) { const int row = row0 + ai * 128 + (2 * mh + mm) * 16; rs[mm] = sh[row] * alpha;
; #pragma unroll
;                     for (int bj = 0; bj < 2; ++bj) { const size_t off = (size_t)row * DM + col0 + bj * 128; pa[mm][bj] = *(const f32x4*)(res + off); pb[mm][bj] = *(const f32x4*)(res + off + 4); } }
; #pragma unroll
;                 for (int mm = 0; mm < 2; ++mm) {
;                     const int m = 2 * mh + mm, row = row0 + ai * 128 + m * 16; float ss = 0.f;
; #pragma unroll
;                     for (int bj = 0; bj < 2; ++bj) {
;                         const size_t off = (size_t)row * DM + col0 + bj * 128; f32x4 v0, v1;
; #pragma unroll
;                         for (int e = 0; e < 4; ++e) { v0[e] = pa[mm][bj][e] + (float)acc[ai][bj][m][0][e] * rs[mm] * s0[bj][e]; v1[e] = pb[mm][bj][e] + (float)acc[ai][bj][m][1][e] * rs[mm] * s1[bj][e]; }
;                         if (out) { *(f32x4*)(out + off) = v0; *(f32x4*)(out + off + 4) = v1; }
;                         if (ob) { u32x4 w; w.x = cvt_pk_bf16(v0[0], v0[1]); w.y = cvt_pk_bf16(v0[2], v0[3]); w.z = cvt_pk_bf16(v1[0], v1[1]); w.w = cvt_pk_bf16(v1[2], v1[3]); *(u32x4*)(ob + blk_off(row, col0 + bj * 128, KT4)) = w; }
;                         ss += (v0[0] * v0[0] + v0[1] * v0[1]) + (v0[2] * v0[2] + v0[3] * v0[3]) + (v1[0] * v1[0] + v1[1] * v1[1]) + (v1[2] * v1[2] + v1[3] * v1[3]);
;                     }
;                     ss += __shfl_xor(ss, 16); ss += __shfl_xor(ss, 32);
;                     if (fq == 0 && racc) atomicAdd(racc + row, (u64)(ss * 4294967296.0f));
.LBB0_4171:
	v_lshl_add_u32 v174, s47, 8, v1
	v_lshl_or_b32 v204, s48, 8, v177
	v_cvt_f32_i32_e32 v215, v134
	v_ashrrev_i32_e32 v175, 31, v174
	v_lshl_add_u64 v[66:67], v[174:175], 2, s[8:9]
	v_ashrrev_i32_e32 v205, 31, v204
	global_load_dword v183, v[66:67], off
	v_lshlrev_b64 v[66:67], 2, v[204:205]
	v_lshl_add_u64 v[70:71], s[10:11], 0, v[66:67]
	global_load_dwordx4 v[74:77], v[70:71], off offset:16 nt
	global_load_dwordx4 v[78:81], v[70:71], off nt
	v_lshlrev_b64 v[68:69], 14, v[174:175]
	v_lshl_add_u64 v[172:173], s[76:77], 0, v[66:67]
	v_lshl_add_u64 v[146:147], v[172:173], 0, v[68:69]
	global_load_dwordx4 v[184:187], v[146:147], off nt
	global_load_dwordx4 v[188:191], v[146:147], off offset:16 nt
	global_load_dwordx4 v[66:69], v[70:71], off offset:528 nt
	s_nop 0
	global_load_dwordx4 v[70:73], v[70:71], off offset:512 nt
	s_nop 0
	global_load_dwordx4 v[192:195], v[146:147], off offset:512 nt
	global_load_dwordx4 v[196:199], v[146:147], off offset:528 nt
	v_add_u32_e32 v134, 16, v174
	v_cvt_f32_i32_e32 v212, v140
	v_cvt_f32_i32_e32 v217, v135
	v_lshlrev_b32_e32 v140, 7, v174
	v_ashrrev_i32_e32 v135, 31, v134
	v_cvt_f32_i32_e32 v203, v138
	v_cvt_f32_i32_e32 v210, v139
	v_cvt_f32_i32_e32 v214, v141
	v_and_b32_e32 v138, 63, v204
	v_ashrrev_i32_e32 v139, 2, v174
	v_and_b32_e32 v206, 0x7f80, v140
	v_lshlrev_b64 v[140:141], 14, v[134:135]
	v_cvt_f32_i32_e32 v202, v142
	v_cvt_f32_i32_e32 v205, v143
	v_and_b32_e32 v218, 0xffffffc0, v139
	v_lshlrev_b32_e32 v162, 1, v138
	v_lshl_add_u64 v[138:139], v[134:135], 2, s[8:9]
	v_lshl_add_u64 v[142:143], v[172:173], 0, v[140:141]
	v_cvt_f32_i32_e32 v211, v144
	v_cvt_f32_i32_e32 v213, v145
	global_load_dword v182, v[138:139], off
	global_load_dwordx4 v[146:149], v[142:143], off offset:16 nt
	global_load_dwordx4 v[150:153], v[142:143], off nt
	s_nop 0
	global_load_dwordx4 v[138:141], v[142:143], off offset:528 nt
	s_nop 0
	global_load_dwordx4 v[142:145], v[142:143], off offset:512 nt
	v_cvt_f32_i32_e32 v216, v130
	v_ashrrev_i32_e32 v130, 6, v204
	v_add_u32_e32 v200, v218, v130
	v_ashrrev_i32_e32 v201, 31, v200
	v_lshlrev_b64 v[200:201], 15, v[200:201]
	v_mov_b32_e32 v207, v163
	v_lshl_add_u64 v[200:201], s[72:73], 0, v[200:201]
	v_lshl_add_u64 v[200:201], v[200:201], 0, v[206:207]
	v_lshl_add_u64 v[208:209], v[200:201], 0, v[162:163]
	v_cvt_f32_i32_e32 v137, v137
	v_cvt_f32_i32_e32 v131, v131
	v_cvt_f32_i32_e32 v136, v136
	v_cvt_f32_i32_e32 v132, v132
	v_cvt_f32_i32_e32 v133, v133
	s_waitcnt vmcnt(0)
	v_mul_f32_e32 v183, 0.5, v183
	v_mul_f32_e32 v200, v183, v202
	v_mul_f32_e32 v202, v183, v205
	v_mul_f32_e32 v205, v183, v211
	v_mul_f32_e32 v211, v183, v213
	v_mul_f32_e32 v201, v183, v203
	v_mul_f32_e32 v203, v183, v210
	v_fma_f32 v185, v79, v202, v185
	v_fmac_f32_e32 v187, v81, v211
	v_mul_f32_e32 v210, v183, v212
	v_mul_f32_e32 v212, v183, v214
	v_fma_f32 v184, v78, v200, v184
	v_fma_f32 v188, v74, v201, v188
	v_fma_f32 v189, v75, v203, v189
	v_fma_f32 v186, v80, v205, v186
	v_cvt_pk_bf16_f32 v200, v184, v185
	v_cvt_pk_bf16_f32 v201, v186, v187
	v_mul_f32_e32 v185, v185, v185
	v_mul_f32_e32 v187, v187, v187
	v_fmac_f32_e32 v191, v77, v212
	v_cvt_pk_bf16_f32 v202, v188, v189
	v_mul_f32_e32 v189, v189, v189
	v_fmac_f32_e32 v185, v184, v184
	v_fmac_f32_e32 v187, v186, v186
	v_fma_f32 v190, v76, v210, v190
	v_cvt_pk_bf16_f32 v203, v190, v191
	v_mul_f32_e32 v191, v191, v191
	v_fmac_f32_e32 v189, v188, v188
	v_add_f32_e32 v184, v185, v187
	v_fmac_f32_e32 v191, v190, v190
	v_add_f32_e32 v184, v189, v184
	v_add_f32_e32 v188, v191, v184
	v_mul_f32_e32 v184, v183, v217
	v_mul_f32_e32 v137, v183, v137
	v_mul_f32_e32 v213, v183, v215
	v_fma_f32 v189, v71, v184, v193
	v_mul_f32_e32 v131, v183, v131
	v_mul_f32_e32 v136, v183, v136
	v_fmac_f32_e32 v195, v73, v137
	v_mul_f32_e32 v214, v183, v216
	v_fma_f32 v192, v70, v213, v192
	v_fma_f32 v131, v67, v131, v197
	v_fma_f32 v136, v72, v136, v194
	v_mul_f32_e32 v132, v183, v132
	v_mul_f32_e32 v133, v183, v133
	v_mul_f32_e32 v137, v189, v189
	v_mul_f32_e32 v183, v195, v195
	v_fma_f32 v196, v66, v214, v196
	global_store_dwordx4 v[208:209], v[200:203], off
	v_cvt_pk_bf16_f32 v184, v192, v189
	v_cvt_pk_bf16_f32 v185, v136, v195
	v_cvt_pk_bf16_f32 v186, v196, v131
	v_fmac_f32_e32 v137, v192, v192
	v_fmac_f32_e32 v183, v136, v136
	v_mul_f32_e32 v131, v131, v131
	v_fmac_f32_e32 v199, v69, v133
	v_add_f32_e32 v136, v137, v183
	v_fmac_f32_e32 v131, v196, v196
	v_fma_f32 v132, v68, v132, v198
	v_add_f32_e32 v131, v136, v131
	v_mul_f32_e32 v136, v199, v199
	v_fmac_f32_e32 v136, v132, v132
	v_cvt_pk_bf16_f32 v187, v132, v199
	v_add_f32_e32 v131, v136, v131
	v_and_b32_e32 v132, 64, v181
	v_add_f32_e32 v183, v188, v131
	v_xor_b32_e32 v131, 16, v181
	v_add_u32_e32 v190, 64, v132
	v_cmp_lt_i32_e32 vcc, v131, v190
	v_add_u32_e32 v133, 0x80, v204
	s_nop 0
	v_cndmask_b32_e32 v131, v181, v131, vcc
	v_lshlrev_b32_e32 v132, 2, v131
	ds_bpermute_b32 v191, v132, v183
	v_ashrrev_i32_e32 v131, 6, v133
	v_xor_b32_e32 v133, 32, v181
	v_add_u32_e32 v136, v131, v218
	v_cmp_lt_i32_e32 vcc, v133, v190
	v_ashrrev_i32_e32 v137, 31, v136
	v_lshlrev_b64 v[188:189], 15, v[136:137]
	v_cndmask_b32_e32 v133, v181, v133, vcc
	s_waitcnt lgkmcnt(0)
	v_add_f32_e32 v136, v183, v191
	v_lshlrev_b32_e32 v133, 2, v133
	ds_bpermute_b32 v137, v133, v136
	v_lshl_add_u64 v[188:189], s[72:73], 0, v[188:189]
	v_lshl_add_u64 v[188:189], v[188:189], 0, v[206:207]
	v_lshl_add_u64 v[188:189], v[188:189], 0, v[162:163]
	global_store_dwordx4 v[188:189], v[184:187], off
	s_and_saveexec_b64 s[20:21], s[2:3]
	s_cbranch_execz .LBB0_4173
	s_waitcnt lgkmcnt(0)
	v_add_f32_e32 v136, v136, v137
	v_mul_f32_e32 v136, 0x4f800000, v136
	v_trunc_f32_e32 v136, v136
	v_mul_f32_e32 v137, 0x2f800000, v136
	v_floor_f32_e32 v137, v137
	v_fmac_f32_e32 v136, 0xcf800000, v137
	v_cvt_u32_f32_e32 v136, v136
	v_cvt_u32_f32_e32 v137, v137
	v_lshl_add_u64 v[184:185], v[174:175], 3, s[12:13]
	global_atomic_add_x2 v[184:185], v[136:137], off

; __host__ __device__ __forceinline__ size_t blk_off(int r, int k, int KT) { return ((size_t)((r >> 8) * KT + (k >> 6)) * 256 + (size_t)(r & 255)) * 64 + (size_t)(k & 63); }
; __device__ __forceinline__ unsigned cvt_pk_bf16(float lo, float hi) { unsigned r; asm volatile("v_cvt_pk_bf16_f32 %0, %1, %2" : "=v"(r) : "v"(lo), "v"(hi)); return r; }
;     __device__ __forceinline__ void operator()(const i32x4 (&acc)[2][2][4][2], const pg8::Unit& u, int wr, int wc, int fr, int fq) const {
;     ...
;                 f32x4 pa[2][2], pb[2][2]; float rs[2];
; #pragma unroll
;                 for (int mm = 0; mm < 2; ++mm) { const int row = row0 + ai * 128 + (2 * mh + mm) * 16; rs[mm] = sh[row] * alpha;
; #pragma unroll
;                     for (int bj = 0; bj < 2; ++bj) { const size_t off = (size_t)row * DM + col0 + bj * 128; pa[mm][bj] = *(const f32x4*)(res + off); pb[mm][bj] = *(const f32x4*)(res + off + 4); } }
; #pragma unroll
;                 for (int mm = 0; mm < 2; ++mm) {
;                     const int m = 2 * mh + mm, row = row0 + ai * 128 + m * 16; float ss = 0.f;
; #pragma unroll
;                     for (int bj = 0; bj < 2; ++bj) {
;                         const size_t off = (size_t)row * DM + col0 + bj * 128; f32x4 v0, v1;
; #pragma unroll
;                         for (int e = 0; e < 4; ++e) { v0[e] = pa[mm][bj][e] + (float)acc[ai][bj][m][0][e] * rs[mm] * s0[bj][e]; v1[e] = pb[mm][bj][e] + (float)acc[ai][bj][m][1][e] * rs[mm] * s1[bj][e]; }
;                         if (out) { *(f32x4*)(out + off) = v0; *(f32x4*)(out + off + 4) = v1; }
;                         if (ob) { u32x4 w; w.x = cvt_pk_bf16(v0[0], v0[1]); w.y = cvt_pk_bf16(v0[2], v0[3]); w.z = cvt_pk_bf16(v1[0], v1[1]); w.w = cvt_pk_bf16(v1[2], v1[3]); *(u32x4*)(ob + blk_off(row, col0 + bj * 128, KT4)) = w; }
;                         ss += (v0[0] * v0[0] + v0[1] * v0[1]) + (v0[2] * v0[2] + v0[3] * v0[3]) + (v1[0] * v1[0] + v1[1] * v1[1]) + (v1[2] * v1[2] + v1[3] * v1[3]);
;                     }
;                     ss += __shfl_xor(ss, 16); ss += __shfl_xor(ss, 32);
;                     if (fq == 0 && racc) atomicAdd(racc + row, (u64)(ss * 4294967296.0f));
.LBB0_4175:
	s_or_b64 exec, exec, s[20:21]
	v_add_u32_e32 v116, 32, v174
	v_ashrrev_i32_e32 v117, 31, v116
	s_waitcnt lgkmcnt(0)
	v_lshl_add_u64 v[114:115], v[116:117], 2, s[8:9]
	global_load_dword v119, v[114:115], off
	v_lshlrev_b64 v[114:115], 14, v[116:117]
	v_lshl_add_u64 v[114:115], v[172:173], 0, v[114:115]
	global_load_dwordx4 v[120:123], v[114:115], off nt
	global_load_dwordx4 v[124:127], v[114:115], off offset:16 nt
	global_load_dwordx4 v[134:137], v[114:115], off offset:512 nt
	global_load_dwordx4 v[138:141], v[114:115], off offset:528 nt
	v_add_u32_e32 v114, 48, v174
	v_ashrrev_i32_e32 v115, 31, v114
	v_cvt_f32_i32_e32 v175, v102
	v_cvt_f32_i32_e32 v183, v103
	v_cvt_f32_i32_e32 v186, v100
	v_cvt_f32_i32_e32 v188, v101
	v_ashrrev_i32_e32 v102, 2, v116
	v_lshlrev_b32_e32 v103, 7, v116
	v_lshlrev_b64 v[100:101], 14, v[114:115]
	v_cvt_f32_i32_e32 v182, v98
	v_cvt_f32_i32_e32 v184, v99
	v_lshl_add_u64 v[98:99], v[114:115], 2, s[8:9]
	v_and_b32_e32 v189, 0xffffffc0, v102
	v_and_b32_e32 v128, 0x7f80, v103
	v_lshl_add_u64 v[102:103], v[172:173], 0, v[100:101]
	v_cvt_f32_i32_e32 v144, v110
	v_cvt_f32_i32_e32 v145, v106
	v_cvt_f32_i32_e32 v148, v111
	v_cvt_f32_i32_e32 v149, v107
	v_cvt_f32_i32_e32 v150, v112
	v_cvt_f32_i32_e32 v151, v108
	v_cvt_f32_i32_e32 v152, v113
	v_cvt_f32_i32_e32 v153, v109
	v_cvt_f32_i32_e32 v185, v104
	v_cvt_f32_i32_e32 v187, v105
	global_load_dword v118, v[98:99], off
	global_load_dwordx4 v[106:109], v[102:103], off offset:16 nt
	global_load_dwordx4 v[110:113], v[102:103], off nt
	s_nop 0
	global_load_dwordx4 v[98:101], v[102:103], off offset:528 nt
	s_nop 0
	global_load_dwordx4 v[102:105], v[102:103], off offset:512 nt
	v_add_u32_e32 v142, v189, v130
	v_ashrrev_i32_e32 v143, 31, v142
	v_lshlrev_b64 v[142:143], 15, v[142:143]
	v_mov_b32_e32 v129, v163
	v_lshl_add_u64 v[142:143], s[72:73], 0, v[142:143]
	v_lshl_add_u64 v[142:143], v[142:143], 0, v[128:129]
	v_lshl_add_u64 v[146:147], v[142:143], 0, v[162:163]
	s_waitcnt vmcnt(9)
	v_mul_f32_e32 v119, 0.5, v119
	v_mul_f32_e32 v142, v119, v144
	v_mul_f32_e32 v144, v119, v148
	v_mul_f32_e32 v148, v119, v150
	v_mul_f32_e32 v150, v119, v152
	v_mul_f32_e32 v143, v119, v145
	v_mul_f32_e32 v145, v119, v149
	s_waitcnt vmcnt(8)
	v_fma_f32 v121, v79, v144, v121
	v_fmac_f32_e32 v123, v81, v150
	v_fma_f32 v120, v78, v142, v120
	s_waitcnt vmcnt(7)
	v_fma_f32 v124, v74, v143, v124
	v_fma_f32 v125, v75, v145, v125
	v_fma_f32 v122, v80, v148, v122
	v_cvt_pk_bf16_f32 v142, v120, v121
	v_cvt_pk_bf16_f32 v143, v122, v123
	v_mul_f32_e32 v121, v121, v121
	v_mul_f32_e32 v123, v123, v123
	v_mul_f32_e32 v152, v119, v175
	v_mul_f32_e32 v175, v119, v183
	v_cvt_pk_bf16_f32 v144, v124, v125
	v_mul_f32_e32 v125, v125, v125
	v_fmac_f32_e32 v121, v120, v120
	v_fmac_f32_e32 v123, v122, v122
	v_mul_f32_e32 v122, v119, v187
	v_mul_f32_e32 v149, v119, v151
	v_mul_f32_e32 v151, v119, v153
	v_mul_f32_e32 v153, v119, v182
	v_mul_f32_e32 v182, v119, v184
	v_mul_f32_e32 v183, v119, v185
	v_mul_f32_e32 v184, v119, v186
	s_waitcnt vmcnt(6)
	v_fma_f32 v135, v71, v175, v135
	v_fmac_f32_e32 v125, v124, v124
	v_add_f32_e32 v120, v121, v123
	v_fmac_f32_e32 v137, v73, v122
	v_mul_f32_e32 v119, v119, v188
	v_fma_f32 v134, v70, v152, v134
	v_fma_f32 v136, v72, v183, v136
	v_add_f32_e32 v120, v125, v120
	s_waitcnt vmcnt(5)
	v_fmac_f32_e32 v141, v69, v119
	v_mul_f32_e32 v119, v135, v135
	v_mul_f32_e32 v125, v137, v137
	v_fma_f32 v139, v67, v182, v139
	v_fmac_f32_e32 v119, v134, v134
	v_fmac_f32_e32 v125, v136, v136
	v_fma_f32 v138, v66, v153, v138
	v_add_f32_e32 v119, v119, v125
	v_mul_f32_e32 v125, v139, v139
	v_fmac_f32_e32 v127, v77, v151
	v_fmac_f32_e32 v125, v138, v138
	v_fma_f32 v126, v76, v149, v126
	v_cvt_pk_bf16_f32 v145, v126, v127
	v_mul_f32_e32 v127, v127, v127
	v_fma_f32 v121, v68, v184, v140
	v_add_f32_e32 v119, v119, v125
	v_mul_f32_e32 v125, v141, v141
	v_fmac_f32_e32 v127, v126, v126
	v_fmac_f32_e32 v125, v121, v121
	v_add_f32_e32 v120, v127, v120
	v_add_f32_e32 v119, v125, v119
	v_add_f32_e32 v119, v120, v119
	global_store_dwordx4 v[146:147], v[142:145], off
	v_cvt_pk_bf16_f32 v122, v134, v135
	ds_bpermute_b32 v134, v132, v119
	v_add_u32_e32 v120, v189, v131
	v_cvt_pk_bf16_f32 v123, v136, v137
	v_cvt_pk_bf16_f32 v124, v138, v139
	v_cvt_pk_bf16_f32 v125, v121, v141
	v_ashrrev_i32_e32 v121, 31, v120
	s_waitcnt lgkmcnt(0)
	v_add_f32_e32 v119, v119, v134
	v_lshlrev_b64 v[126:127], 15, v[120:121]
	ds_bpermute_b32 v120, v133, v119
	v_lshl_add_u64 v[126:127], s[72:73], 0, v[126:127]
	v_lshl_add_u64 v[126:127], v[126:127], 0, v[128:129]
	v_lshl_add_u64 v[126:127], v[126:127], 0, v[162:163]
	global_store_dwordx4 v[126:127], v[122:125], off
	s_and_saveexec_b64 s[20:21], s[2:3]
	s_cbranch_execz .LBB0_4177
	s_waitcnt lgkmcnt(0)
	v_add_f32_e32 v119, v119, v120
	v_mul_f32_e32 v119, 0x4f800000, v119
	v_trunc_f32_e32 v119, v119
	v_mul_f32_e32 v120, 0x2f800000, v119
	v_floor_f32_e32 v121, v120
	v_fmac_f32_e32 v119, 0xcf800000, v121
	v_cvt_u32_f32_e32 v120, v119
	v_cvt_u32_f32_e32 v121, v121
	v_lshl_add_u64 v[116:117], v[116:117], 3, s[12:13]
	global_atomic_add_x2 v[116:117], v[120:121], off

; __host__ __device__ __forceinline__ size_t blk_off(int r, int k, int KT) { return ((size_t)((r >> 8) * KT + (k >> 6)) * 256 + (size_t)(r & 255)) * 64 + (size_t)(k & 63); }
; __device__ __forceinline__ unsigned cvt_pk_bf16(float lo, float hi) { unsigned r; asm volatile("v_cvt_pk_bf16_f32 %0, %1, %2" : "=v"(r) : "v"(lo), "v"(hi)); return r; }
;     __device__ __forceinline__ void operator()(const i32x4 (&acc)[2][2][4][2], const pg8::Unit& u, int wr, int wc, int fr, int fq) const {
;     ...
;                 f32x4 pa[2][2], pb[2][2]; float rs[2];
; #pragma unroll
;                 for (int mm = 0; mm < 2; ++mm) { const int row = row0 + ai * 128 + (2 * mh + mm) * 16; rs[mm] = sh[row] * alpha;
; #pragma unroll
;                     for (int bj = 0; bj < 2; ++bj) { const size_t off = (size_t)row * DM + col0 + bj * 128; pa[mm][bj] = *(const f32x4*)(res + off); pb[mm][bj] = *(const f32x4*)(res + off + 4); } }
; #pragma unroll
;                 for (int mm = 0; mm < 2; ++mm) {
;                     const int m = 2 * mh + mm, row = row0 + ai * 128 + m * 16; float ss = 0.f;
; #pragma unroll
;                     for (int bj = 0; bj < 2; ++bj) {
;                         const size_t off = (size_t)row * DM + col0 + bj * 128; f32x4 v0, v1;
; #pragma unroll
;                         for (int e = 0; e < 4; ++e) { v0[e] = pa[mm][bj][e] + (float)acc[ai][bj][m][0][e] * rs[mm] * s0[bj][e]; v1[e] = pb[mm][bj][e] + (float)acc[ai][bj][m][1][e] * rs[mm] * s1[bj][e]; }
;                         if (out) { *(f32x4*)(out + off) = v0; *(f32x4*)(out + off + 4) = v1; }
;                         if (ob) { u32x4 w; w.x = cvt_pk_bf16(v0[0], v0[1]); w.y = cvt_pk_bf16(v0[2], v0[3]); w.z = cvt_pk_bf16(v1[0], v1[1]); w.w = cvt_pk_bf16(v1[2], v1[3]); *(u32x4*)(ob + blk_off(row, col0 + bj * 128, KT4)) = w; }
;                         ss += (v0[0] * v0[0] + v0[1] * v0[1]) + (v0[2] * v0[2] + v0[3] * v0[3]) + (v1[0] * v1[0] + v1[1] * v1[1]) + (v1[2] * v1[2] + v1[3] * v1[3]);
;                     }
;                     ss += __shfl_xor(ss, 16); ss += __shfl_xor(ss, 32);
;                     if (fq == 0 && racc) atomicAdd(racc + row, (u64)(ss * 4294967296.0f));
.LBB0_4179:
	s_or_b64 exec, exec, s[20:21]
	v_add_u32_e32 v84, 0x80, v174
	v_ashrrev_i32_e32 v85, 31, v84
	s_waitcnt lgkmcnt(0)
	v_lshl_add_u64 v[82:83], v[84:85], 2, s[8:9]
	global_load_dword v87, v[82:83], off
	v_lshlrev_b64 v[82:83], 14, v[84:85]
	v_lshl_add_u64 v[82:83], v[172:173], 0, v[82:83]
	global_load_dwordx4 v[88:91], v[82:83], off nt
	global_load_dwordx4 v[92:95], v[82:83], off offset:16 nt
	global_load_dwordx4 v[96:99], v[82:83], off offset:512 nt
	global_load_dwordx4 v[100:103], v[82:83], off offset:528 nt
	v_add_u32_e32 v82, 0x90, v174
	v_ashrrev_i32_e32 v83, 31, v82
	v_cvt_f32_i32_e32 v118, v54
	v_cvt_f32_i32_e32 v120, v55
	v_cvt_f32_i32_e32 v123, v52
	v_cvt_f32_i32_e32 v125, v53
	v_ashrrev_i32_e32 v54, 2, v84
	v_lshlrev_b32_e32 v55, 7, v84
	v_lshlrev_b64 v[52:53], 14, v[82:83]
	v_cvt_f32_i32_e32 v119, v50
	v_cvt_f32_i32_e32 v121, v51
	v_lshl_add_u64 v[50:51], v[82:83], 2, s[8:9]
	v_and_b32_e32 v126, 0xffffffc0, v54
	v_and_b32_e32 v108, 0x7f80, v55
	v_lshl_add_u64 v[54:55], v[172:173], 0, v[52:53]
	v_cvt_f32_i32_e32 v106, v62
	v_cvt_f32_i32_e32 v107, v58
	v_cvt_f32_i32_e32 v112, v63
	v_cvt_f32_i32_e32 v113, v59
	v_cvt_f32_i32_e32 v114, v64
	v_cvt_f32_i32_e32 v115, v60
	v_cvt_f32_i32_e32 v116, v65
	v_cvt_f32_i32_e32 v117, v61
	v_cvt_f32_i32_e32 v122, v56
	v_cvt_f32_i32_e32 v124, v57
	global_load_dword v86, v[50:51], off
	global_load_dwordx4 v[58:61], v[54:55], off offset:16 nt
	global_load_dwordx4 v[62:65], v[54:55], off nt
	s_nop 0
	global_load_dwordx4 v[50:53], v[54:55], off offset:528 nt
	s_nop 0
	global_load_dwordx4 v[54:57], v[54:55], off offset:512 nt
	v_add_u32_e32 v104, v126, v130
	v_ashrrev_i32_e32 v105, 31, v104
	v_lshlrev_b64 v[104:105], 15, v[104:105]
	v_mov_b32_e32 v109, v163
	v_lshl_add_u64 v[104:105], s[72:73], 0, v[104:105]
	v_lshl_add_u64 v[104:105], v[104:105], 0, v[108:109]
	v_lshl_add_u64 v[110:111], v[104:105], 0, v[162:163]
	s_waitcnt vmcnt(9)
	v_mul_f32_e32 v87, 0.5, v87
	v_mul_f32_e32 v104, v87, v106
	v_mul_f32_e32 v106, v87, v112
	v_mul_f32_e32 v112, v87, v114
	v_mul_f32_e32 v114, v87, v116
	v_mul_f32_e32 v105, v87, v107
	v_mul_f32_e32 v107, v87, v113
	s_waitcnt vmcnt(8)
	v_fma_f32 v89, v79, v106, v89
	v_fmac_f32_e32 v91, v81, v114
	v_fma_f32 v88, v78, v104, v88
	s_waitcnt vmcnt(7)
	v_fma_f32 v92, v74, v105, v92
	v_fma_f32 v93, v75, v107, v93
	v_fma_f32 v90, v80, v112, v90
	v_cvt_pk_bf16_f32 v104, v88, v89
	v_cvt_pk_bf16_f32 v105, v90, v91
	v_mul_f32_e32 v89, v89, v89
	v_mul_f32_e32 v91, v91, v91
	v_mul_f32_e32 v116, v87, v118
	v_mul_f32_e32 v118, v87, v120
	v_cvt_pk_bf16_f32 v106, v92, v93
	v_mul_f32_e32 v93, v93, v93
	v_fmac_f32_e32 v89, v88, v88
	v_fmac_f32_e32 v91, v90, v90
	v_mul_f32_e32 v90, v87, v124
	v_mul_f32_e32 v113, v87, v115
	v_mul_f32_e32 v115, v87, v117
	v_mul_f32_e32 v117, v87, v119
	v_mul_f32_e32 v119, v87, v121
	v_mul_f32_e32 v120, v87, v122
	v_mul_f32_e32 v121, v87, v123
	s_waitcnt vmcnt(6)
	v_fma_f32 v97, v71, v118, v97
	v_fmac_f32_e32 v93, v92, v92
	v_add_f32_e32 v88, v89, v91
	v_fmac_f32_e32 v99, v73, v90
	v_mul_f32_e32 v87, v87, v125
	v_fma_f32 v96, v70, v116, v96
	v_fma_f32 v98, v72, v120, v98
	v_add_f32_e32 v88, v93, v88
	s_waitcnt vmcnt(5)
	v_fmac_f32_e32 v103, v69, v87
	v_mul_f32_e32 v87, v97, v97
	v_mul_f32_e32 v93, v99, v99
	v_fma_f32 v101, v67, v119, v101
	v_fmac_f32_e32 v87, v96, v96
	v_fmac_f32_e32 v93, v98, v98
	v_fma_f32 v100, v66, v117, v100
	v_add_f32_e32 v87, v87, v93
	v_mul_f32_e32 v93, v101, v101
	v_fmac_f32_e32 v95, v77, v115
	v_fmac_f32_e32 v93, v100, v100
	v_fma_f32 v94, v76, v113, v94
	v_cvt_pk_bf16_f32 v107, v94, v95
	v_mul_f32_e32 v95, v95, v95
	v_fma_f32 v89, v68, v121, v102
	v_add_f32_e32 v87, v87, v93
	v_mul_f32_e32 v93, v103, v103
	v_fmac_f32_e32 v95, v94, v94
	v_fmac_f32_e32 v93, v89, v89
	v_add_f32_e32 v88, v95, v88
	v_add_f32_e32 v87, v93, v87
	v_add_f32_e32 v87, v88, v87
	global_store_dwordx4 v[110:111], v[104:107], off
	v_cvt_pk_bf16_f32 v90, v96, v97
	ds_bpermute_b32 v96, v132, v87
	v_add_u32_e32 v88, v126, v131
	v_cvt_pk_bf16_f32 v91, v98, v99
	v_cvt_pk_bf16_f32 v92, v100, v101
	v_cvt_pk_bf16_f32 v93, v89, v103
	v_ashrrev_i32_e32 v89, 31, v88
	s_waitcnt lgkmcnt(0)
	v_add_f32_e32 v87, v87, v96
	v_lshlrev_b64 v[94:95], 15, v[88:89]
	ds_bpermute_b32 v88, v133, v87
	v_lshl_add_u64 v[94:95], s[72:73], 0, v[94:95]
	v_lshl_add_u64 v[94:95], v[94:95], 0, v[108:109]
	v_lshl_add_u64 v[94:95], v[94:95], 0, v[162:163]
	global_store_dwordx4 v[94:95], v[90:93], off
	s_and_saveexec_b64 s[20:21], s[2:3]
	s_cbranch_execz .LBB0_4181
	s_waitcnt lgkmcnt(0)
	v_add_f32_e32 v87, v87, v88
	v_mul_f32_e32 v87, 0x4f800000, v87
	v_trunc_f32_e32 v87, v87
	v_mul_f32_e32 v88, 0x2f800000, v87
	v_floor_f32_e32 v89, v88
	v_fmac_f32_e32 v87, 0xcf800000, v89
	v_cvt_u32_f32_e32 v88, v87
	v_cvt_u32_f32_e32 v89, v89
	v_lshl_add_u64 v[84:85], v[84:85], 3, s[12:13]
	global_atomic_add_x2 v[84:85], v[88:89], off

; __host__ __device__ __forceinline__ size_t blk_off(int r, int k, int KT) { return ((size_t)((r >> 8) * KT + (k >> 6)) * 256 + (size_t)(r & 255)) * 64 + (size_t)(k & 63); }
; __device__ __forceinline__ unsigned cvt_pk_bf16(float lo, float hi) { unsigned r; asm volatile("v_cvt_pk_bf16_f32 %0, %1, %2" : "=v"(r) : "v"(lo), "v"(hi)); return r; }
;     __device__ __forceinline__ void operator()(const i32x4 (&acc)[2][2][4][2], const pg8::Unit& u, int wr, int wc, int fr, int fq) const {
;     ...
;                 f32x4 pa[2][2], pb[2][2]; float rs[2];
; #pragma unroll
;                 for (int mm = 0; mm < 2; ++mm) { const int row = row0 + ai * 128 + (2 * mh + mm) * 16; rs[mm] = sh[row] * alpha;
; #pragma unroll
;                     for (int bj = 0; bj < 2; ++bj) { const size_t off = (size_t)row * DM + col0 + bj * 128; pa[mm][bj] = *(const f32x4*)(res + off); pb[mm][bj] = *(const f32x4*)(res + off + 4); } }
; #pragma unroll
;                 for (int mm = 0; mm < 2; ++mm) {
;                     const int m = 2 * mh + mm, row = row0 + ai * 128 + m * 16; float ss = 0.f;
; #pragma unroll
;                     for (int bj = 0; bj < 2; ++bj) {
;                         const size_t off = (size_t)row * DM + col0 + bj * 128; f32x4 v0, v1;
; #pragma unroll
;                         for (int e = 0; e < 4; ++e) { v0[e] = pa[mm][bj][e] + (float)acc[ai][bj][m][0][e] * rs[mm] * s0[bj][e]; v1[e] = pb[mm][bj][e] + (float)acc[ai][bj][m][1][e] * rs[mm] * s1[bj][e]; }
;                         if (out) { *(f32x4*)(out + off) = v0; *(f32x4*)(out + off + 4) = v1; }
;                         if (ob) { u32x4 w; w.x = cvt_pk_bf16(v0[0], v0[1]); w.y = cvt_pk_bf16(v0[2], v0[3]); w.z = cvt_pk_bf16(v1[0], v1[1]); w.w = cvt_pk_bf16(v1[2], v1[3]); *(u32x4*)(ob + blk_off(row, col0 + bj * 128, KT4)) = w; }
;                         ss += (v0[0] * v0[0] + v0[1] * v0[1]) + (v0[2] * v0[2] + v0[3] * v0[3]) + (v1[0] * v1[0] + v1[1] * v1[1]) + (v1[2] * v1[2] + v1[3] * v1[3]);
;                     }
;                     ss += __shfl_xor(ss, 16); ss += __shfl_xor(ss, 32);
;                     if (fq == 0 && racc) atomicAdd(racc + row, (u64)(ss * 4294967296.0f));
.LBB0_4183:
	s_or_b64 exec, exec, s[20:21]
	v_add_u32_e32 v36, 0xa0, v174
	v_ashrrev_i32_e32 v37, 31, v36
	s_waitcnt lgkmcnt(0)
	v_lshl_add_u64 v[34:35], v[36:37], 2, s[8:9]
	global_load_dword v39, v[34:35], off
	v_lshlrev_b64 v[34:35], 14, v[36:37]
	v_lshl_add_u64 v[34:35], v[172:173], 0, v[34:35]
	global_load_dwordx4 v[40:43], v[34:35], off nt
	global_load_dwordx4 v[44:47], v[34:35], off offset:16 nt
	global_load_dwordx4 v[48:51], v[34:35], off offset:512 nt
	global_load_dwordx4 v[52:55], v[34:35], off offset:528 nt
	v_add_u32_e32 v34, 0xb0, v174
	v_ashrrev_i32_e32 v35, 31, v34
	v_cvt_f32_i32_e32 v86, v22
	v_cvt_f32_i32_e32 v88, v23
	v_cvt_f32_i32_e32 v91, v20
	v_cvt_f32_i32_e32 v93, v21
	v_ashrrev_i32_e32 v22, 2, v36
	v_lshlrev_b32_e32 v23, 7, v36
	v_lshlrev_b64 v[20:21], 14, v[34:35]
	v_cvt_f32_i32_e32 v87, v18
	v_cvt_f32_i32_e32 v89, v19
	v_lshl_add_u64 v[18:19], v[34:35], 2, s[8:9]
	v_and_b32_e32 v94, 0xffffffc0, v22
	v_and_b32_e32 v60, 0x7f80, v23
	v_lshl_add_u64 v[22:23], v[172:173], 0, v[20:21]
	v_cvt_f32_i32_e32 v58, v30
	v_cvt_f32_i32_e32 v59, v26
	v_cvt_f32_i32_e32 v64, v31
	v_cvt_f32_i32_e32 v65, v27
	v_cvt_f32_i32_e32 v82, v32
	v_cvt_f32_i32_e32 v83, v28
	v_cvt_f32_i32_e32 v84, v33
	v_cvt_f32_i32_e32 v85, v29
	v_cvt_f32_i32_e32 v90, v24
	v_cvt_f32_i32_e32 v92, v25
	global_load_dword v38, v[18:19], off
	global_load_dwordx4 v[26:29], v[22:23], off offset:16 nt
	global_load_dwordx4 v[30:33], v[22:23], off nt
	s_nop 0
	global_load_dwordx4 v[18:21], v[22:23], off offset:528 nt
	s_nop 0
	global_load_dwordx4 v[22:25], v[22:23], off offset:512 nt
	v_add_u32_e32 v56, v94, v130
	v_ashrrev_i32_e32 v57, 31, v56
	v_lshlrev_b64 v[56:57], 15, v[56:57]
	v_mov_b32_e32 v61, v163
	v_lshl_add_u64 v[56:57], s[72:73], 0, v[56:57]
	v_lshl_add_u64 v[56:57], v[56:57], 0, v[60:61]
	v_lshl_add_u64 v[62:63], v[56:57], 0, v[162:163]
	s_waitcnt vmcnt(9)
	v_mul_f32_e32 v39, 0.5, v39
	v_mul_f32_e32 v56, v39, v58
	v_mul_f32_e32 v58, v39, v64
	v_mul_f32_e32 v64, v39, v82
	v_mul_f32_e32 v82, v39, v84
	v_mul_f32_e32 v57, v39, v59
	v_mul_f32_e32 v59, v39, v65
	s_waitcnt vmcnt(8)
	v_fma_f32 v41, v79, v58, v41
	v_fmac_f32_e32 v43, v81, v82
	v_fma_f32 v40, v78, v56, v40
	s_waitcnt vmcnt(7)
	v_fma_f32 v44, v74, v57, v44
	v_fma_f32 v45, v75, v59, v45
	v_fma_f32 v42, v80, v64, v42
	v_cvt_pk_bf16_f32 v56, v40, v41
	v_cvt_pk_bf16_f32 v57, v42, v43
	v_mul_f32_e32 v41, v41, v41
	v_mul_f32_e32 v43, v43, v43
	v_mul_f32_e32 v84, v39, v86
	v_mul_f32_e32 v86, v39, v88
	v_cvt_pk_bf16_f32 v58, v44, v45
	v_mul_f32_e32 v45, v45, v45
	v_fmac_f32_e32 v41, v40, v40
	v_fmac_f32_e32 v43, v42, v42
	v_mul_f32_e32 v42, v39, v92
	v_mul_f32_e32 v65, v39, v83
	v_mul_f32_e32 v83, v39, v85
	v_mul_f32_e32 v85, v39, v87
	v_mul_f32_e32 v87, v39, v89
	v_mul_f32_e32 v88, v39, v90
	v_mul_f32_e32 v89, v39, v91
	s_waitcnt vmcnt(6)
	v_fma_f32 v49, v71, v86, v49
	v_fmac_f32_e32 v45, v44, v44
	v_add_f32_e32 v40, v41, v43
	v_fmac_f32_e32 v51, v73, v42
	v_mul_f32_e32 v39, v39, v93
	v_fma_f32 v48, v70, v84, v48
	v_fma_f32 v50, v72, v88, v50
	v_add_f32_e32 v40, v45, v40
	s_waitcnt vmcnt(5)
	v_fmac_f32_e32 v55, v69, v39
	v_mul_f32_e32 v39, v49, v49
	v_mul_f32_e32 v45, v51, v51
	v_fma_f32 v53, v67, v87, v53
	v_fmac_f32_e32 v39, v48, v48
	v_fmac_f32_e32 v45, v50, v50
	v_fma_f32 v52, v66, v85, v52
	v_add_f32_e32 v39, v39, v45
	v_mul_f32_e32 v45, v53, v53
	v_fmac_f32_e32 v47, v77, v83
	v_fmac_f32_e32 v45, v52, v52
	v_fma_f32 v46, v76, v65, v46
	v_cvt_pk_bf16_f32 v59, v46, v47
	v_mul_f32_e32 v47, v47, v47
	v_fma_f32 v41, v68, v89, v54
	v_add_f32_e32 v39, v39, v45
	v_mul_f32_e32 v45, v55, v55
	v_fmac_f32_e32 v47, v46, v46
	v_fmac_f32_e32 v45, v41, v41
	v_add_f32_e32 v40, v47, v40
	v_add_f32_e32 v39, v45, v39
	v_add_f32_e32 v39, v40, v39
	global_store_dwordx4 v[62:63], v[56:59], off
	v_cvt_pk_bf16_f32 v42, v48, v49
	ds_bpermute_b32 v48, v132, v39
	v_add_u32_e32 v40, v94, v131
	v_cvt_pk_bf16_f32 v43, v50, v51
	v_cvt_pk_bf16_f32 v44, v52, v53
	v_cvt_pk_bf16_f32 v45, v41, v55
	v_ashrrev_i32_e32 v41, 31, v40
	s_waitcnt lgkmcnt(0)
	v_add_f32_e32 v39, v39, v48
	v_lshlrev_b64 v[46:47], 15, v[40:41]
	ds_bpermute_b32 v40, v133, v39
	v_lshl_add_u64 v[46:47], s[72:73], 0, v[46:47]
	v_lshl_add_u64 v[46:47], v[46:47], 0, v[60:61]
	v_lshl_add_u64 v[46:47], v[46:47], 0, v[162:163]
	global_store_dwordx4 v[46:47], v[42:45], off
	s_and_saveexec_b64 s[20:21], s[2:3]
	s_cbranch_execz .LBB0_4185
	s_waitcnt lgkmcnt(0)
	v_add_f32_e32 v39, v39, v40
	v_mul_f32_e32 v39, 0x4f800000, v39
	v_trunc_f32_e32 v39, v39
	v_mul_f32_e32 v40, 0x2f800000, v39
	v_floor_f32_e32 v41, v40
	v_fmac_f32_e32 v39, 0xcf800000, v41
	v_cvt_u32_f32_e32 v40, v39
	v_cvt_u32_f32_e32 v41, v41
	v_lshl_add_u64 v[36:37], v[36:37], 3, s[12:13]
	global_atomic_add_x2 v[36:37], v[40:41], off
